# MLA attention: K-fragment LDS reads software-pipelined 3 pairs ahead in QK phase (uses v238-253), L1 tile DMA issues interleaved into QK
# speedup vs baseline: 1.0121x; 1.0121x over previous
.LBB0_1425:
	s_cmp_lg_u32 0, -1
	s_cselect_b32 s0, 0, 0
	s_add_i32 s1, s0, 0x8000
	ds_read_b128 v[178:181], v211
	ds_read_b128 v[214:217], v211 offset:12288
	ds_read_b128 v[238:241], v210
	ds_read_b128 v[242:245], v210 offset:12288
	ds_read_b128 v[246:249], v209
	ds_read_b128 v[250:253], v209 offset:12288
	ds_read_b128 v[218:221], v193
	ds_read_b128 v[222:225], v193 offset:1024
	ds_read_b128 v[226:229], v193 offset:2048
	ds_read_b128 v[230:233], v193 offset:3072
	s_waitcnt lgkmcnt(9)
	v_mfma_f32_32x32x16_bf16 v[114:129], v[178:181], v[158:161], v[82:97]
	s_waitcnt lgkmcnt(8)
	v_mfma_f32_32x32x16_bf16 v[98:113], v[214:217], v[158:161], v[82:97]
	ds_read_b128 v[178:181], v208
	ds_read_b128 v[214:217], v208 offset:12288
	s_add_i32 s8, s74, s1
	s_mov_b32 s9, m0
	s_mov_b32 m0, s8
	s_nop 0
	global_load_lds_dwordx4 v[168:169], off
	s_mov_b32 m0, s9
	s_waitcnt lgkmcnt(9)
	v_mfma_f32_32x32x16_bf16 v[114:129], v[238:241], v[154:157], v[114:129]
	s_waitcnt lgkmcnt(8)
	v_mfma_f32_32x32x16_bf16 v[98:113], v[242:245], v[154:157], v[98:113]
	ds_read_b128 v[238:241], v207
	ds_read_b128 v[242:245], v207 offset:12288
	s_add_i32 s8, s75, s1
	s_mov_b32 s9, m0
	s_mov_b32 m0, s8
	s_nop 0
	global_load_lds_dwordx4 v[170:171], off
	s_mov_b32 m0, s9
	s_waitcnt lgkmcnt(9)
	v_mfma_f32_32x32x16_bf16 v[114:129], v[246:249], v[150:153], v[114:129]
	s_waitcnt lgkmcnt(8)
	v_mfma_f32_32x32x16_bf16 v[98:113], v[250:253], v[150:153], v[98:113]
	ds_read_b128 v[246:249], v206
	ds_read_b128 v[250:253], v206 offset:12288
	s_add_i32 s1, s5, s1
	s_mov_b32 s8, m0
	s_mov_b32 m0, s1
	s_nop 0
	global_load_lds_dwordx4 v[172:173], off
	s_mov_b32 m0, s8
	s_waitcnt lgkmcnt(5)
	v_mfma_f32_32x32x16_bf16 v[114:129], v[178:181], v[146:149], v[114:129]
	s_waitcnt lgkmcnt(4)
	v_mfma_f32_32x32x16_bf16 v[98:113], v[214:217], v[146:149], v[98:113]
	ds_read_b128 v[178:181], v205
	ds_read_b128 v[214:217], v205 offset:12288
	s_add_i32 s1, s86, s0
	s_mov_b32 s8, m0
	s_mov_b32 m0, s1
	s_nop 0
	global_load_lds_dwordx4 v[174:175], off
	s_mov_b32 m0, s8
	s_waitcnt lgkmcnt(5)
	v_mfma_f32_32x32x16_bf16 v[114:129], v[238:241], v[142:145], v[114:129]
	s_waitcnt lgkmcnt(4)
	v_mfma_f32_32x32x16_bf16 v[98:113], v[242:245], v[142:145], v[98:113]
	ds_read_b128 v[238:241], v204
	ds_read_b128 v[242:245], v204 offset:12288
	s_add_i32 s0, s3, s0
	s_mov_b32 s1, m0
	s_mov_b32 m0, s0
	s_nop 0
	global_load_lds_dwordx4 v[176:177], off
	s_mov_b32 m0, s1
	s_waitcnt lgkmcnt(5)
	v_mfma_f32_32x32x16_bf16 v[114:129], v[246:249], v[138:141], v[114:129]
	s_waitcnt lgkmcnt(4)
	v_mfma_f32_32x32x16_bf16 v[98:113], v[250:253], v[138:141], v[98:113]
	ds_read_b128 v[246:249], v203
	ds_read_b128 v[250:253], v203 offset:12288
	s_waitcnt lgkmcnt(5)
	v_mfma_f32_32x32x16_bf16 v[114:129], v[178:181], v[134:137], v[114:129]
	s_waitcnt lgkmcnt(4)
	v_mfma_f32_32x32x16_bf16 v[98:113], v[214:217], v[134:137], v[98:113]
	ds_read_b128 v[178:181], v202
	ds_read_b128 v[214:217], v202 offset:12288
	s_waitcnt lgkmcnt(5)
	v_mfma_f32_32x32x16_bf16 v[114:129], v[238:241], v[130:133], v[114:129]
	s_waitcnt lgkmcnt(4)
	v_mfma_f32_32x32x16_bf16 v[98:113], v[242:245], v[130:133], v[98:113]
	ds_read_b128 v[238:241], v201
	ds_read_b128 v[242:245], v201 offset:12288
	s_waitcnt lgkmcnt(5)
	v_mfma_f32_32x32x16_bf16 v[114:129], v[246:249], v[218:221], v[114:129]
	s_waitcnt lgkmcnt(4)
	v_mfma_f32_32x32x16_bf16 v[98:113], v[250:253], v[218:221], v[98:113]
	ds_read_b128 v[246:249], v200
	ds_read_b128 v[250:253], v200 offset:12288
	s_waitcnt lgkmcnt(5)
	v_mfma_f32_32x32x16_bf16 v[114:129], v[178:181], v[222:225], v[114:129]
	s_waitcnt lgkmcnt(4)
	v_mfma_f32_32x32x16_bf16 v[98:113], v[214:217], v[222:225], v[98:113]
	s_waitcnt lgkmcnt(3)
	v_mfma_f32_32x32x16_bf16 v[114:129], v[238:241], v[226:229], v[114:129]
	s_waitcnt lgkmcnt(2)
	v_mfma_f32_32x32x16_bf16 v[98:113], v[242:245], v[226:229], v[98:113]
	s_waitcnt lgkmcnt(1)
	v_mfma_f32_32x32x16_bf16 v[114:129], v[246:249], v[230:233], v[114:129]
	s_waitcnt lgkmcnt(0)
	v_mfma_f32_32x32x16_bf16 v[98:113], v[250:253], v[230:233], v[98:113]
	s_sub_i32 s0, s12, 64
	s_cmp_le_i32 s0, s96
	s_cbranch_scc1 .LBB0_1427
	v_add_u32_e32 v165, 0x5b, v212
	v_cmp_lt_i32_e32 vcc, -1, v165
	s_nop 4
	v_cndmask_b32_e32 v114, v185, v114, vcc
	v_cmp_lt_i32_e32 vcc, 31, v165
	v_add_u32_e32 v165, 0x5a, v212
	s_nop 0
	v_cndmask_b32_e32 v98, v185, v98, vcc
	v_cmp_lt_i32_e32 vcc, -1, v165
	s_nop 1
	v_cndmask_b32_e32 v115, v185, v115, vcc
	v_cmp_lt_i32_e32 vcc, 31, v165
	v_add_u32_e32 v165, 0x59, v212
	s_nop 0
	v_cndmask_b32_e32 v99, v185, v99, vcc
	v_cmp_lt_i32_e32 vcc, -1, v165
	s_nop 1
	v_cndmask_b32_e32 v116, v185, v116, vcc
	v_cmp_lt_i32_e32 vcc, 31, v165
	v_add_u32_e32 v165, 0x58, v212
	s_nop 0
	v_cndmask_b32_e32 v100, v185, v100, vcc
	v_cmp_lt_i32_e32 vcc, -1, v165
	s_nop 1
	v_cndmask_b32_e32 v117, v185, v117, vcc
	v_cmp_lt_i32_e32 vcc, 31, v165
	v_add_u32_e32 v165, 0x53, v212
	s_nop 0
	v_cndmask_b32_e32 v101, v185, v101, vcc
	v_cmp_lt_i32_e32 vcc, -1, v165
	s_nop 1
	v_cndmask_b32_e32 v118, v185, v118, vcc
	v_cmp_lt_i32_e32 vcc, 31, v165
	v_add_u32_e32 v165, 0x52, v212
	s_nop 0
	v_cndmask_b32_e32 v102, v185, v102, vcc
	v_cmp_lt_i32_e32 vcc, -1, v165
	s_nop 1
	v_cndmask_b32_e32 v119, v185, v119, vcc
	v_cmp_lt_i32_e32 vcc, 31, v165
	v_add_u32_e32 v165, 0x51, v212
	s_nop 0
	v_cndmask_b32_e32 v103, v185, v103, vcc
	v_cmp_lt_i32_e32 vcc, -1, v165
	s_nop 1
	v_cndmask_b32_e32 v120, v185, v120, vcc
	v_cmp_lt_i32_e32 vcc, 31, v165
	v_add_u32_e32 v165, 0x50, v212
	s_nop 0
	v_cndmask_b32_e32 v104, v185, v104, vcc
	v_cmp_lt_i32_e32 vcc, -1, v165
	s_nop 1
	v_cndmask_b32_e32 v121, v185, v121, vcc
	v_cmp_lt_i32_e32 vcc, 31, v165
	v_add_u32_e32 v165, 0x4b, v212
	s_nop 0
	v_cndmask_b32_e32 v105, v185, v105, vcc
	v_cmp_lt_i32_e32 vcc, -1, v165
	s_nop 1
	v_cndmask_b32_e32 v122, v185, v122, vcc
	v_cmp_lt_i32_e32 vcc, 31, v165
	v_add_u32_e32 v165, 0x4a, v212
	s_nop 0
	v_cndmask_b32_e32 v106, v185, v106, vcc
	v_cmp_lt_i32_e32 vcc, -1, v165
	s_nop 1
	v_cndmask_b32_e32 v123, v185, v123, vcc
	v_cmp_lt_i32_e32 vcc, 31, v165
	v_add_u32_e32 v165, 0x49, v212
	s_nop 0
	v_cndmask_b32_e32 v107, v185, v107, vcc
	v_cmp_lt_i32_e32 vcc, -1, v165
	s_nop 1
	v_cndmask_b32_e32 v124, v185, v124, vcc
	v_cmp_lt_i32_e32 vcc, 31, v165
	v_add_u32_e32 v165, 0x48, v212
	s_nop 0
	v_cndmask_b32_e32 v108, v185, v108, vcc
	v_cmp_lt_i32_e32 vcc, -1, v165
	s_nop 1
	v_cndmask_b32_e32 v125, v185, v125, vcc
	v_cmp_lt_i32_e32 vcc, 31, v165
	v_add_u32_e32 v165, 0x43, v212
	s_nop 0
	v_cndmask_b32_e32 v109, v185, v109, vcc
	v_cmp_lt_i32_e32 vcc, -1, v165
	s_nop 1
	v_cndmask_b32_e32 v126, v185, v126, vcc
	v_cmp_lt_i32_e32 vcc, 31, v165
	v_add_u32_e32 v165, 0x42, v212
	s_nop 0
	v_cndmask_b32_e32 v110, v185, v110, vcc
	v_cmp_lt_i32_e32 vcc, -1, v165
	s_nop 1
	v_cndmask_b32_e32 v127, v185, v127, vcc
	v_cmp_lt_i32_e32 vcc, 31, v165
	v_add_u32_e32 v165, 0x41, v212
	s_nop 0
	v_cndmask_b32_e32 v111, v185, v111, vcc
	v_cmp_lt_i32_e32 vcc, -1, v165
	s_nop 1
	v_cndmask_b32_e32 v128, v185, v128, vcc
	v_cmp_lt_i32_e32 vcc, 31, v165
	v_add_u32_e32 v165, 64, v212
	s_nop 0
	v_cndmask_b32_e32 v112, v185, v112, vcc
	v_cmp_lt_i32_e32 vcc, -1, v165
	s_nop 1
	v_cndmask_b32_e32 v129, v185, v129, vcc
	v_cmp_lt_i32_e32 vcc, 31, v165
	s_nop 1
	v_cndmask_b32_e32 v113, v185, v113, vcc

.LBB0_1434:
	ds_read_b128 v[178:181], v194 offset:32768
	ds_read_b128 v[216:219], v194 offset:45056
	ds_read_b128 v[238:241], v195 offset:32768
	ds_read_b128 v[242:245], v195 offset:45056
	ds_read_b128 v[246:249], v196 offset:32768
	ds_read_b128 v[250:253], v196 offset:45056
	ds_read_b128 v[220:223], v193
	ds_read_b128 v[224:227], v193 offset:1024
	ds_read_b128 v[228:231], v193 offset:2048
	ds_read_b128 v[232:235], v193 offset:3072
	s_waitcnt lgkmcnt(9)
	v_mfma_f32_32x32x16_bf16 v[114:129], v[178:181], v[158:161], v[82:97]
	s_waitcnt lgkmcnt(8)
	v_mfma_f32_32x32x16_bf16 v[98:113], v[216:219], v[158:161], v[82:97]
	ds_read_b128 v[178:181], v197 offset:32768
	ds_read_b128 v[216:219], v197 offset:45056
	s_waitcnt lgkmcnt(9)
	v_mfma_f32_32x32x16_bf16 v[114:129], v[238:241], v[154:157], v[114:129]
	s_waitcnt lgkmcnt(8)
	v_mfma_f32_32x32x16_bf16 v[98:113], v[242:245], v[154:157], v[98:113]
	ds_read_b128 v[238:241], v194 offset:32896
	ds_read_b128 v[242:245], v194 offset:45184
	s_waitcnt lgkmcnt(9)
	v_mfma_f32_32x32x16_bf16 v[114:129], v[246:249], v[150:153], v[114:129]
	s_waitcnt lgkmcnt(8)
	v_mfma_f32_32x32x16_bf16 v[98:113], v[250:253], v[150:153], v[98:113]
	ds_read_b128 v[246:249], v195 offset:32896
	ds_read_b128 v[250:253], v195 offset:45184
	s_waitcnt lgkmcnt(5)
	v_mfma_f32_32x32x16_bf16 v[114:129], v[178:181], v[146:149], v[114:129]
	s_waitcnt lgkmcnt(4)
	v_mfma_f32_32x32x16_bf16 v[98:113], v[216:219], v[146:149], v[98:113]
	ds_read_b128 v[178:181], v196 offset:32896
	ds_read_b128 v[216:219], v196 offset:45184
	s_waitcnt lgkmcnt(5)
	v_mfma_f32_32x32x16_bf16 v[114:129], v[238:241], v[142:145], v[114:129]
	s_waitcnt lgkmcnt(4)
	v_mfma_f32_32x32x16_bf16 v[98:113], v[242:245], v[142:145], v[98:113]
	ds_read_b128 v[238:241], v197 offset:32896
	ds_read_b128 v[242:245], v197 offset:45184
	s_waitcnt lgkmcnt(5)
	v_mfma_f32_32x32x16_bf16 v[114:129], v[246:249], v[138:141], v[114:129]
	s_waitcnt lgkmcnt(4)
	v_mfma_f32_32x32x16_bf16 v[98:113], v[250:253], v[138:141], v[98:113]
	ds_read_b128 v[246:249], v194 offset:33024
	ds_read_b128 v[250:253], v194 offset:45312
	s_waitcnt lgkmcnt(5)
	v_mfma_f32_32x32x16_bf16 v[114:129], v[178:181], v[134:137], v[114:129]
	s_waitcnt lgkmcnt(4)
	v_mfma_f32_32x32x16_bf16 v[98:113], v[216:219], v[134:137], v[98:113]
	ds_read_b128 v[178:181], v195 offset:33024
	ds_read_b128 v[216:219], v195 offset:45312
	s_waitcnt lgkmcnt(5)
	v_mfma_f32_32x32x16_bf16 v[114:129], v[238:241], v[130:133], v[114:129]
	s_waitcnt lgkmcnt(4)
	v_mfma_f32_32x32x16_bf16 v[98:113], v[242:245], v[130:133], v[98:113]
	ds_read_b128 v[238:241], v196 offset:33024
	ds_read_b128 v[242:245], v196 offset:45312
	s_waitcnt lgkmcnt(5)
	v_mfma_f32_32x32x16_bf16 v[114:129], v[246:249], v[220:223], v[114:129]
	s_waitcnt lgkmcnt(4)
	v_mfma_f32_32x32x16_bf16 v[98:113], v[250:253], v[220:223], v[98:113]
	ds_read_b128 v[246:249], v197 offset:33024
	ds_read_b128 v[250:253], v197 offset:45312
	s_waitcnt lgkmcnt(5)
	v_mfma_f32_32x32x16_bf16 v[114:129], v[178:181], v[224:227], v[114:129]
	s_waitcnt lgkmcnt(4)
	v_mfma_f32_32x32x16_bf16 v[98:113], v[216:219], v[224:227], v[98:113]
	s_waitcnt lgkmcnt(3)
	v_mfma_f32_32x32x16_bf16 v[114:129], v[238:241], v[228:231], v[114:129]
	s_waitcnt lgkmcnt(2)
	v_mfma_f32_32x32x16_bf16 v[98:113], v[242:245], v[228:231], v[98:113]
	s_waitcnt lgkmcnt(1)
	v_mfma_f32_32x32x16_bf16 v[114:129], v[246:249], v[232:235], v[114:129]
	s_waitcnt lgkmcnt(0)
	v_mfma_f32_32x32x16_bf16 v[98:113], v[250:253], v[232:235], v[98:113]
	s_cmp_le_i32 s12, s96
	s_cbranch_scc1 .LBB0_1436
	v_add_u32_e32 v165, 27, v212
	v_cmp_lt_i32_e32 vcc, -1, v165
	s_nop 5
	v_cndmask_b32_e32 v114, v185, v114, vcc
	v_cmp_lt_i32_e32 vcc, 31, v165
	v_add_u32_e32 v165, 26, v212
	s_nop 0
	v_cndmask_b32_e32 v98, v185, v98, vcc
	v_cmp_lt_i32_e32 vcc, -1, v165
	s_nop 1
	v_cndmask_b32_e32 v115, v185, v115, vcc
	v_cmp_lt_i32_e32 vcc, 31, v165
	v_add_u32_e32 v165, 25, v212
	s_nop 0
	v_cndmask_b32_e32 v99, v185, v99, vcc
	v_cmp_lt_i32_e32 vcc, -1, v165
	s_nop 1
	v_cndmask_b32_e32 v116, v185, v116, vcc
	v_cmp_lt_i32_e32 vcc, 31, v165
	v_add_u32_e32 v165, 24, v212
	s_nop 0
	v_cndmask_b32_e32 v100, v185, v100, vcc
	v_cmp_lt_i32_e32 vcc, -1, v165
	s_nop 1
	v_cndmask_b32_e32 v117, v185, v117, vcc
	v_cmp_lt_i32_e32 vcc, 31, v165
	v_add_u32_e32 v165, 19, v212
	s_nop 0
	v_cndmask_b32_e32 v101, v185, v101, vcc
	v_cmp_lt_i32_e32 vcc, -1, v165
	s_nop 1
	v_cndmask_b32_e32 v118, v185, v118, vcc
	v_cmp_lt_i32_e32 vcc, 31, v165
	v_add_u32_e32 v165, 18, v212
	s_nop 0
	v_cndmask_b32_e32 v102, v185, v102, vcc
	v_cmp_lt_i32_e32 vcc, -1, v165
	s_nop 1
	v_cndmask_b32_e32 v119, v185, v119, vcc
	v_cmp_lt_i32_e32 vcc, 31, v165
	v_add_u32_e32 v165, 17, v212
	s_nop 0
	v_cndmask_b32_e32 v103, v185, v103, vcc
	v_cmp_lt_i32_e32 vcc, -1, v165
	s_nop 1
	v_cndmask_b32_e32 v120, v185, v120, vcc
	v_cmp_lt_i32_e32 vcc, 31, v165
	v_add_u32_e32 v165, 16, v212
	s_nop 0
	v_cndmask_b32_e32 v104, v185, v104, vcc
	v_cmp_lt_i32_e32 vcc, -1, v165
	s_nop 1
	v_cndmask_b32_e32 v121, v185, v121, vcc
	v_cmp_lt_i32_e32 vcc, 31, v165
	v_add_u32_e32 v165, 11, v212
	s_nop 0
	v_cndmask_b32_e32 v105, v185, v105, vcc
	v_cmp_lt_i32_e32 vcc, -1, v165
	s_nop 1
	v_cndmask_b32_e32 v122, v185, v122, vcc
	v_cmp_lt_i32_e32 vcc, 31, v165
	v_add_u32_e32 v165, 10, v212
	s_nop 0
	v_cndmask_b32_e32 v106, v185, v106, vcc
	v_cmp_lt_i32_e32 vcc, -1, v165
	s_nop 1
	v_cndmask_b32_e32 v123, v185, v123, vcc
	v_cmp_lt_i32_e32 vcc, 31, v165
	v_add_u32_e32 v165, 9, v212
	s_nop 0
	v_cndmask_b32_e32 v107, v185, v107, vcc
	v_cmp_lt_i32_e32 vcc, -1, v165
	s_nop 1
	v_cndmask_b32_e32 v124, v185, v124, vcc
	v_cmp_lt_i32_e32 vcc, 31, v165
	v_add_u32_e32 v165, 8, v212
	s_nop 0
	v_cndmask_b32_e32 v108, v185, v108, vcc
	v_cmp_lt_i32_e32 vcc, -1, v165
	s_nop 1
	v_cndmask_b32_e32 v125, v185, v125, vcc
	v_cmp_lt_i32_e32 vcc, 31, v165
	v_add_u32_e32 v165, 3, v212
	s_nop 0
	v_cndmask_b32_e32 v109, v185, v109, vcc
	v_cmp_lt_i32_e32 vcc, -1, v165
	s_nop 1
	v_cndmask_b32_e32 v126, v185, v126, vcc
	v_cmp_lt_i32_e32 vcc, 31, v165
	v_add_u32_e32 v165, 2, v212
	s_nop 0
	v_cndmask_b32_e32 v110, v185, v110, vcc
	v_cmp_lt_i32_e32 vcc, -1, v165
	s_nop 1
	v_cndmask_b32_e32 v127, v185, v127, vcc
	v_cmp_lt_i32_e32 vcc, 31, v165
	v_add_u32_e32 v165, 1, v212
	s_nop 0
	v_cndmask_b32_e32 v111, v185, v111, vcc
	v_cmp_lt_i32_e32 vcc, -1, v165
	s_nop 1
	v_cndmask_b32_e32 v128, v185, v128, vcc
	v_cmp_lt_i32_e32 vcc, 31, v165
	s_nop 1
	v_cndmask_b32_e32 v112, v185, v112, vcc
	v_cmp_lt_i32_e32 vcc, -1, v212
	s_nop 1
	v_cndmask_b32_e32 v129, v185, v129, vcc
	v_cmp_lt_i32_e32 vcc, 31, v212
	s_nop 1
	v_cndmask_b32_e32 v113, v185, v113, vcc

	.amdhsa_kernel _Z8yoco_fwd4Args
		.amdhsa_group_segment_fixed_size 0
		.amdhsa_private_segment_fixed_size 0
		.amdhsa_kernarg_size 416
		.amdhsa_user_sgpr_count 2
		.amdhsa_user_sgpr_dispatch_ptr 0
		.amdhsa_user_sgpr_queue_ptr 0
		.amdhsa_user_sgpr_kernarg_segment_ptr 1
		.amdhsa_user_sgpr_dispatch_id 0
		.amdhsa_user_sgpr_kernarg_preload_length 0
		.amdhsa_user_sgpr_kernarg_preload_offset 0
		.amdhsa_user_sgpr_private_segment_size 0
		.amdhsa_uses_dynamic_stack 0
		.amdhsa_enable_private_segment 0
		.amdhsa_system_sgpr_workgroup_id_x 1
		.amdhsa_system_sgpr_workgroup_id_y 0
		.amdhsa_system_sgpr_workgroup_id_z 0
		.amdhsa_system_sgpr_workgroup_info 0
		.amdhsa_system_vgpr_workitem_id 2
		.amdhsa_next_free_vgpr 254
		.amdhsa_next_free_sgpr 98
		.amdhsa_accum_offset 256
		.amdhsa_reserve_vcc 1
		.amdhsa_float_round_mode_32 0
		.amdhsa_float_round_mode_16_64 0
		.amdhsa_float_denorm_mode_32 3
		.amdhsa_float_denorm_mode_16_64 3
		.amdhsa_dx10_clamp 1
		.amdhsa_ieee_mode 1
		.amdhsa_fp16_overflow 0
		.amdhsa_tg_split 0
		.amdhsa_exception_fp_ieee_invalid_op 0
		.amdhsa_exception_fp_denorm_src 0
		.amdhsa_exception_fp_ieee_div_zero 0
		.amdhsa_exception_fp_ieee_overflow 0
		.amdhsa_exception_fp_ieee_underflow 0
		.amdhsa_exception_fp_ieee_inexact 0
		.amdhsa_exception_int_div_zero 0
	.end_amdhsa_kernel

amdhsa.kernels:
  - .agpr_count:     0
    .args:
      - .offset:         0
        .size:           160
        .value_kind:     by_value
      - .offset:         160
        .size:           4
        .value_kind:     hidden_block_count_x
      - .offset:         164
        .size:           4
        .value_kind:     hidden_block_count_y
      - .offset:         168
        .size:           4
        .value_kind:     hidden_block_count_z
      - .offset:         172
        .size:           2
        .value_kind:     hidden_group_size_x
      - .offset:         174
        .size:           2
        .value_kind:     hidden_group_size_y
      - .offset:         176
        .size:           2
        .value_kind:     hidden_group_size_z
      - .offset:         178
        .size:           2
        .value_kind:     hidden_remainder_x
      - .offset:         180
        .size:           2
        .value_kind:     hidden_remainder_y
      - .offset:         182
        .size:           2
        .value_kind:     hidden_remainder_z
      - .offset:         200
        .size:           8
        .value_kind:     hidden_global_offset_x
      - .offset:         208
        .size:           8
        .value_kind:     hidden_global_offset_y
      - .offset:         216
        .size:           8
        .value_kind:     hidden_global_offset_z
      - .offset:         224
        .size:           2
        .value_kind:     hidden_grid_dims
      - .offset:         248
        .size:           8
        .value_kind:     hidden_multigrid_sync_arg
      - .offset:         280
        .size:           4
        .value_kind:     hidden_dynamic_lds_size
    .group_segment_fixed_size: 0
    .kernarg_segment_align: 8
    .kernarg_segment_size: 416
    .language:       OpenCL C
    .language_version:
      - 2
      - 0
    .max_flat_workgroup_size: 512
    .name:           _Z8yoco_fwd4Args
    .private_segment_fixed_size: 0
    .sgpr_count:     104
    .sgpr_spill_count: 19
    .symbol:         _Z8yoco_fwd4Args.kd
    .uniform_work_group_size: 1
    .uses_dynamic_stack: false
    .vgpr_count:     254
    .vgpr_spill_count: 0
    .wavefront_size: 64
